# XCD-aware tile index remap in all GEMM tile loops (n-tiles of one m-tile share an XCD L2) on top of attention DMA-wait removal
# speedup vs baseline: 1.0124x; 1.0124x over previous
.LBB0_176:
	s_lshr_b32 s0, s16, 8
	s_lshl_b32 s0, s0, 2
	s_bfe_u32 s6, s16, 0x20003
	s_add_i32 s6, s6, s0
	s_bfe_u32 s0, s16, 0x30005
	s_lshl_b32 s0, s0, 3
	s_and_b32 s1, s16, 7
	s_add_i32 s0, s0, s1
	s_and_b32 s1, s16, 63
	s_cmpk_lt_u32 s16, 0x200
	s_cselect_b32 s6, s6, 8
	s_cselect_b32 s0, s0, s1
	s_lshl_b32 s2, s0, 8
	s_ashr_i32 s3, s2, 31
	s_ashr_i32 s7, s6, 31
	s_lshl_b64 s[0:1], s[6:7], 19
	s_lshl_b64 s[8:9], s[2:3], 11
	v_readlane_b32 s10, v250, 44
	v_readlane_b32 s11, v250, 45
	s_add_u32 s10, s10, s8
	v_mov_b32_e32 v34, v216
	s_addc_u32 s11, s11, s9
	v_readlane_b32 s3, v252, 33
	s_add_u32 s12, s3, s0
	v_lshlrev_b32_e32 v0, 4, v34
	v_readlane_b32 s3, v252, 34
	v_ashrrev_i32_e32 v35, 3, v34
	v_and_b32_e32 v0, 0x70, v0
	s_addc_u32 s13, s3, s1
	v_lshl_or_b32 v0, v35, 11, v0
	v_lshl_add_u64 v[26:27], s[12:13], 0, v[0:1]
	v_add_co_u32_e32 v10, vcc, s52, v26
	v_lshl_add_u64 v[28:29], s[10:11], 0, v[0:1]
	s_nop 0
	v_addc_co_u32_e32 v11, vcc, 0, v27, vcc
	v_add_co_u32_e32 v14, vcc, s52, v28
	global_load_dwordx4 v[2:5], v0, s[12:13]
	global_load_dwordx4 v[6:9], v0, s[10:11]
	v_addc_co_u32_e32 v15, vcc, 0, v29, vcc
	v_add_co_u32_e32 v18, vcc, s56, v26
	global_load_dwordx4 v[10:13], v[10:11], off
	s_nop 0
	global_load_dwordx4 v[14:17], v[14:15], off
	v_addc_co_u32_e32 v19, vcc, 0, v27, vcc
	v_add_co_u32_e32 v22, vcc, s56, v28
	v_lshrrev_b32_e32 v36, 1, v35
	s_nop 0
	v_addc_co_u32_e32 v23, vcc, 0, v29, vcc
	v_add_co_u32_e32 v26, vcc, s57, v26
	global_load_dwordx4 v[18:21], v[18:19], off
	s_nop 0
	global_load_dwordx4 v[22:25], v[22:23], off
	v_addc_co_u32_e32 v27, vcc, 0, v27, vcc
	v_add_co_u32_e32 v30, vcc, s57, v28
	v_xor_b32_e32 v34, v36, v34
	s_nop 0
	v_addc_co_u32_e32 v31, vcc, 0, v29, vcc
	global_load_dwordx4 v[26:29], v[26:27], off
	s_nop 0
	global_load_dwordx4 v[30:33], v[30:31], off
	v_lshlrev_b32_e32 v35, 7, v35
	v_lshlrev_b32_e32 v34, 4, v34
	v_and_or_b32 v174, v34, s55, v35
	v_add_u32_e32 v175, 0x10000, v174
	s_waitcnt vmcnt(0)
	ds_write_b128 v174, v[2:5]
	s_waitcnt vmcnt(6)
	ds_write_b128 v175, v[6:9]
	s_waitcnt vmcnt(5)
	ds_write_b128 v174, v[10:13] offset:8192
	s_waitcnt vmcnt(4)
	ds_write_b128 v175, v[14:17] offset:8192
	s_waitcnt vmcnt(3)
	ds_write_b128 v174, v[18:21] offset:16384
	s_waitcnt vmcnt(2)
	ds_write_b128 v175, v[22:25] offset:16384
	s_waitcnt vmcnt(1)
	ds_write_b128 v174, v[26:29] offset:24576
	s_waitcnt vmcnt(0)
	ds_write_b128 v175, v[30:33] offset:24576
	s_waitcnt lgkmcnt(0)
	s_barrier
	s_and_saveexec_b64 s[10:11], s[4:5]
	s_cbranch_execz .LBB0_178
	v_add_u32_e32 v2, s2, v216
	v_ashrrev_i32_e32 v3, 31, v2
	v_readlane_b32 s12, v250, 46
	v_lshlrev_b64 v[2:3], 6, v[2:3]
	v_readlane_b32 s13, v250, 47
	s_nop 1
	v_lshl_add_u64 v[14:15], s[12:13], 0, v[2:3]
	global_load_dwordx4 v[2:5], v[14:15], off
	global_load_dwordx4 v[6:9], v[14:15], off offset:16
	global_load_dwordx4 v[10:13], v[14:15], off offset:32
	s_nop 0
	global_load_dwordx4 v[14:17], v[14:15], off offset:48
	s_waitcnt vmcnt(3)
	v_mov_b32_e32 v18, v2
	s_waitcnt vmcnt(2)
	v_mov_b32_e32 v19, v6
	v_mov_b32_e32 v6, v3
	v_mov_b32_e32 v2, v4
	v_mov_b32_e32 v3, v8
	v_mov_b32_e32 v8, v5
	s_waitcnt vmcnt(1)
	v_mov_b32_e32 v4, v10
	s_waitcnt vmcnt(0)
	v_mov_b32_e32 v5, v14
	v_mov_b32_e32 v14, v11
	v_pk_add_f32 v[6:7], v[18:19], v[6:7]
	v_mov_b32_e32 v10, v12
	v_mov_b32_e32 v11, v16
	v_pk_add_f32 v[4:5], v[4:5], v[14:15]
	v_pk_add_f32 v[2:3], v[2:3], v[6:7]
	v_mov_b32_e32 v16, v13
	v_pk_add_f32 v[4:5], v[10:11], v[4:5]
	v_pk_add_f32 v[2:3], v[8:9], v[2:3]
	v_pk_add_f32 v[4:5], v[16:17], v[4:5]
	v_add_f32_e32 v2, v2, v3
	v_add_f32_e32 v2, v2, v4
	v_add_f32_e32 v2, v2, v5
	v_fmamk_f32 v2, v2, 0x3a800000, v206
	v_mul_f32_e32 v3, 0x4b800000, v2
	v_cmp_gt_f32_e32 vcc, s58, v2
	s_nop 1
	v_cndmask_b32_e32 v2, v2, v3, vcc
	v_rsq_f32_e32 v2, v2
	s_nop 0
	v_mul_f32_e32 v3, 0x45800000, v2
	v_cndmask_b32_e32 v2, v2, v3, vcc
	ds_write_b32 v222, v2

.LBB0_1123:
	s_bfe_u32 s4, s14, 0x20003
	s_lshr_b32 s0, s14, 5
	s_lshl_b32 s0, s0, 3
	s_and_b32 s1, s14, 7
	s_add_i32 s0, s0, s1
	s_lshl_b32 s2, s0, 8
	s_ashr_i32 s3, s2, 31
	s_ashr_i32 s5, s4, 31
	s_lshl_b64 s[0:1], s[4:5], 19
	s_lshl_b64 s[6:7], s[2:3], 11
	v_readlane_b32 s8, v252, 31
	v_readlane_b32 s9, v252, 32
	s_add_u32 s8, s8, s6
	v_mov_b32_e32 v34, v178
	s_addc_u32 s9, s9, s7
	v_readlane_b32 s3, v252, 49
	s_add_u32 s10, s3, s0
	v_lshlrev_b32_e32 v0, 4, v34
	v_readlane_b32 s3, v252, 50
	v_ashrrev_i32_e32 v35, 3, v34
	v_and_b32_e32 v0, 0x70, v0
	s_addc_u32 s11, s3, s1
	v_lshl_or_b32 v0, v35, 11, v0
	v_lshl_add_u64 v[26:27], s[10:11], 0, v[0:1]
	v_add_co_u32_e32 v10, vcc, s52, v26
	v_lshl_add_u64 v[28:29], s[8:9], 0, v[0:1]
	s_nop 0
	v_addc_co_u32_e32 v11, vcc, 0, v27, vcc
	v_add_co_u32_e32 v14, vcc, s52, v28
	global_load_dwordx4 v[2:5], v0, s[10:11]
	global_load_dwordx4 v[6:9], v0, s[8:9]
	v_addc_co_u32_e32 v15, vcc, 0, v29, vcc
	v_add_co_u32_e32 v18, vcc, s56, v26
	global_load_dwordx4 v[10:13], v[10:11], off
	s_nop 0
	global_load_dwordx4 v[14:17], v[14:15], off
	v_addc_co_u32_e32 v19, vcc, 0, v27, vcc
	v_add_co_u32_e32 v22, vcc, s56, v28
	v_readlane_b32 s8, v250, 9
	s_nop 0
	v_addc_co_u32_e32 v23, vcc, 0, v29, vcc
	v_add_co_u32_e32 v26, vcc, s57, v26
	global_load_dwordx4 v[18:21], v[18:19], off
	s_nop 0
	global_load_dwordx4 v[22:25], v[22:23], off
	v_addc_co_u32_e32 v27, vcc, 0, v27, vcc
	v_add_co_u32_e32 v30, vcc, s57, v28
	v_lshrrev_b32_e32 v36, 1, v35
	s_nop 0
	v_addc_co_u32_e32 v31, vcc, 0, v29, vcc
	global_load_dwordx4 v[26:29], v[26:27], off
	s_nop 0
	global_load_dwordx4 v[30:33], v[30:31], off
	v_readlane_b32 s10, v250, 11
	v_xor_b32_e32 v34, v36, v34
	v_readlane_b32 s11, v250, 12
	s_add_u32 s6, s10, s6
	v_lshlrev_b32_e32 v35, 7, v35
	v_lshlrev_b32_e32 v34, 4, v34
	s_addc_u32 s7, s11, s7
	v_mov_b32_e32 v82, 0
	v_and_or_b32 v198, v34, s55, v35
	v_readlane_b32 s9, v250, 10
	s_add_u32 s8, s10, s0
	s_mov_b32 s3, 0
	v_mov_b32_e32 v83, v82
	v_mov_b32_e32 v84, v82
	v_mov_b32_e32 v85, v82
	v_mov_b32_e32 v86, v82
	v_mov_b32_e32 v87, v82
	v_mov_b32_e32 v88, v82
	v_mov_b32_e32 v89, v82
	v_mov_b32_e32 v90, v82
	v_mov_b32_e32 v91, v82
	v_mov_b32_e32 v92, v82
	v_mov_b32_e32 v93, v82
	v_mov_b32_e32 v94, v82
	v_mov_b32_e32 v95, v82
	v_mov_b32_e32 v96, v82
	v_mov_b32_e32 v97, v82
	v_mov_b32_e32 v66, v82
	v_add_u32_e32 v199, 0x10000, v198
	s_addc_u32 s9, s11, s1
	v_mov_b32_e32 v67, v82
	v_mov_b32_e32 v68, v82
	v_mov_b32_e32 v69, v82
	v_mov_b32_e32 v70, v82
	v_mov_b32_e32 v71, v82
	v_mov_b32_e32 v72, v82
	v_mov_b32_e32 v73, v82
	v_mov_b32_e32 v74, v82
	v_mov_b32_e32 v75, v82
	v_mov_b32_e32 v76, v82
	v_mov_b32_e32 v77, v82
	v_mov_b32_e32 v78, v82
	v_mov_b32_e32 v79, v82
	v_mov_b32_e32 v80, v82
	v_mov_b32_e32 v81, v82
	v_mov_b32_e32 v114, v82
	v_mov_b32_e32 v115, v82
	s_waitcnt vmcnt(7)
	ds_write_b128 v198, v[2:5]
	s_waitcnt vmcnt(6)
	ds_write_b128 v199, v[6:9]
	s_waitcnt vmcnt(5)
	ds_write_b128 v198, v[10:13] offset:8192
	s_waitcnt vmcnt(4)
	ds_write_b128 v199, v[14:17] offset:8192
	s_waitcnt vmcnt(3)
	ds_write_b128 v198, v[18:21] offset:16384
	s_waitcnt vmcnt(2)
	ds_write_b128 v199, v[22:25] offset:16384
	s_waitcnt vmcnt(1)
	ds_write_b128 v198, v[26:29] offset:24576
	s_waitcnt vmcnt(0)
	ds_write_b128 v199, v[30:33] offset:24576
	v_mov_b32_e32 v18, v82
	v_mov_b32_e32 v19, v82
	v_mov_b32_e32 v20, v82
	v_mov_b32_e32 v21, v82
	v_mov_b32_e32 v22, v82
	v_mov_b32_e32 v23, v82
	v_mov_b32_e32 v24, v82
	v_mov_b32_e32 v25, v82
	v_mov_b32_e32 v26, v82
	v_mov_b32_e32 v27, v82
	v_mov_b32_e32 v28, v82
	v_mov_b32_e32 v29, v82
	v_mov_b32_e32 v30, v82
	v_mov_b32_e32 v31, v82
	v_mov_b32_e32 v32, v82
	v_mov_b32_e32 v33, v82
	v_mov_b32_e32 v2, v82
	v_mov_b32_e32 v3, v82
	v_mov_b32_e32 v4, v82
	v_mov_b32_e32 v5, v82
	v_mov_b32_e32 v6, v82
	v_mov_b32_e32 v7, v82
	v_mov_b32_e32 v8, v82
	v_mov_b32_e32 v9, v82
	v_mov_b32_e32 v10, v82
	v_mov_b32_e32 v11, v82
	v_mov_b32_e32 v12, v82
	v_mov_b32_e32 v13, v82
	v_mov_b32_e32 v14, v82
	v_mov_b32_e32 v15, v82
	v_mov_b32_e32 v16, v82
	v_mov_b32_e32 v17, v82
	v_mov_b32_e32 v116, v82
	v_mov_b32_e32 v117, v82
	v_mov_b32_e32 v118, v82
	v_mov_b32_e32 v119, v82
	v_mov_b32_e32 v120, v82
	v_mov_b32_e32 v121, v82
	v_mov_b32_e32 v122, v82
	v_mov_b32_e32 v123, v82
	v_mov_b32_e32 v124, v82
	v_mov_b32_e32 v125, v82
	v_mov_b32_e32 v126, v82
	v_mov_b32_e32 v127, v82
	v_mov_b32_e32 v128, v82
	v_mov_b32_e32 v129, v82
	v_mov_b32_e32 v98, v82
	v_mov_b32_e32 v99, v82
	v_mov_b32_e32 v100, v82
	v_mov_b32_e32 v101, v82
	v_mov_b32_e32 v102, v82
	v_mov_b32_e32 v103, v82
	v_mov_b32_e32 v104, v82
	v_mov_b32_e32 v105, v82
	v_mov_b32_e32 v106, v82
	v_mov_b32_e32 v107, v82
	v_mov_b32_e32 v108, v82
	v_mov_b32_e32 v109, v82
	v_mov_b32_e32 v110, v82
	v_mov_b32_e32 v111, v82
	v_mov_b32_e32 v112, v82
	v_mov_b32_e32 v113, v82
	v_mov_b32_e32 v50, v82
	v_mov_b32_e32 v51, v82
	v_mov_b32_e32 v52, v82
	v_mov_b32_e32 v53, v82
	v_mov_b32_e32 v54, v82
	v_mov_b32_e32 v55, v82
	v_mov_b32_e32 v56, v82
	v_mov_b32_e32 v57, v82
	v_mov_b32_e32 v58, v82
	v_mov_b32_e32 v59, v82
	v_mov_b32_e32 v60, v82
	v_mov_b32_e32 v61, v82
	v_mov_b32_e32 v62, v82
	v_mov_b32_e32 v63, v82
	v_mov_b32_e32 v64, v82
	v_mov_b32_e32 v65, v82
	v_mov_b32_e32 v34, v82
	v_mov_b32_e32 v35, v82
	v_mov_b32_e32 v36, v82
	v_mov_b32_e32 v37, v82
	v_mov_b32_e32 v38, v82
	v_mov_b32_e32 v39, v82
	v_mov_b32_e32 v40, v82
	v_mov_b32_e32 v41, v82
	v_mov_b32_e32 v42, v82
	v_mov_b32_e32 v43, v82
	v_mov_b32_e32 v44, v82
	v_mov_b32_e32 v45, v82
	v_mov_b32_e32 v46, v82
	v_mov_b32_e32 v47, v82
	v_mov_b32_e32 v48, v82
	v_mov_b32_e32 v49, v82
	s_waitcnt lgkmcnt(0)
	s_barrier
	s_branch .LBB0_1125

.LBB0_1241:
	s_lshr_b32 s0, s21, 8
	s_lshl_b32 s0, s0, 2
	s_bfe_u32 s6, s21, 0x20003
	s_add_i32 s6, s6, s0
	s_bfe_u32 s0, s21, 0x30005
	s_lshl_b32 s0, s0, 3
	s_and_b32 s1, s21, 7
	s_add_i32 s0, s0, s1
	s_lshl_b32 s2, s0, 8
	s_ashr_i32 s3, s2, 31
	s_ashr_i32 s7, s6, 31
	s_lshl_b64 s[0:1], s[6:7], 19
	s_lshl_b64 s[8:9], s[2:3], 11
	v_readlane_b32 s10, v250, 44
	v_readlane_b32 s11, v250, 45
	s_add_u32 s10, s10, s8
	v_mov_b32_e32 v34, v198
	s_addc_u32 s11, s11, s9
	s_add_u32 s12, s16, s0
	v_lshlrev_b32_e32 v0, 4, v34
	v_ashrrev_i32_e32 v35, 3, v34
	v_and_b32_e32 v0, 0x70, v0
	s_addc_u32 s13, s17, s1
	v_lshl_or_b32 v0, v35, 11, v0
	v_lshl_add_u64 v[26:27], s[12:13], 0, v[0:1]
	v_add_co_u32_e32 v10, vcc, s52, v26
	v_lshl_add_u64 v[28:29], s[10:11], 0, v[0:1]
	s_nop 0
	v_addc_co_u32_e32 v11, vcc, 0, v27, vcc
	v_add_co_u32_e32 v14, vcc, s52, v28
	global_load_dwordx4 v[2:5], v0, s[12:13]
	global_load_dwordx4 v[6:9], v0, s[10:11]
	v_addc_co_u32_e32 v15, vcc, 0, v29, vcc
	v_add_co_u32_e32 v18, vcc, s56, v26
	global_load_dwordx4 v[10:13], v[10:11], off
	s_nop 0
	global_load_dwordx4 v[14:17], v[14:15], off
	v_addc_co_u32_e32 v19, vcc, 0, v27, vcc
	v_add_co_u32_e32 v22, vcc, s56, v28
	v_lshrrev_b32_e32 v36, 1, v35
	s_nop 0
	v_addc_co_u32_e32 v23, vcc, 0, v29, vcc
	v_add_co_u32_e32 v26, vcc, s57, v26
	global_load_dwordx4 v[18:21], v[18:19], off
	s_nop 0
	global_load_dwordx4 v[22:25], v[22:23], off
	v_addc_co_u32_e32 v27, vcc, 0, v27, vcc
	v_add_co_u32_e32 v30, vcc, s57, v28
	v_xor_b32_e32 v34, v36, v34
	s_nop 0
	v_addc_co_u32_e32 v31, vcc, 0, v29, vcc
	global_load_dwordx4 v[26:29], v[26:27], off
	s_nop 0
	global_load_dwordx4 v[30:33], v[30:31], off
	v_lshlrev_b32_e32 v35, 7, v35
	v_lshlrev_b32_e32 v34, 4, v34
	v_and_or_b32 v174, v34, s55, v35
	v_add_u32_e32 v175, 0x10000, v174
	s_waitcnt vmcnt(0)
	ds_write_b128 v174, v[2:5]
	s_waitcnt vmcnt(6)
	ds_write_b128 v175, v[6:9]
	s_waitcnt vmcnt(5)
	ds_write_b128 v174, v[10:13] offset:8192
	s_waitcnt vmcnt(4)
	ds_write_b128 v175, v[14:17] offset:8192
	s_waitcnt vmcnt(3)
	ds_write_b128 v174, v[18:21] offset:16384
	s_waitcnt vmcnt(2)
	ds_write_b128 v175, v[22:25] offset:16384
	s_waitcnt vmcnt(1)
	ds_write_b128 v174, v[26:29] offset:24576
	s_waitcnt vmcnt(0)
	ds_write_b128 v175, v[30:33] offset:24576
	s_waitcnt lgkmcnt(0)
	s_barrier
	s_and_saveexec_b64 s[10:11], s[4:5]
	s_cbranch_execz .LBB0_1243
	v_add_u32_e32 v2, s2, v198
	v_ashrrev_i32_e32 v3, 31, v2
	v_readlane_b32 s12, v250, 46
	v_lshlrev_b64 v[2:3], 6, v[2:3]
	v_readlane_b32 s13, v250, 47
	s_nop 1
	v_lshl_add_u64 v[14:15], s[12:13], 0, v[2:3]
	global_load_dwordx4 v[2:5], v[14:15], off
	global_load_dwordx4 v[6:9], v[14:15], off offset:16
	global_load_dwordx4 v[10:13], v[14:15], off offset:32
	s_nop 0
	global_load_dwordx4 v[14:17], v[14:15], off offset:48
	s_waitcnt vmcnt(3)
	v_mov_b32_e32 v18, v2
	s_waitcnt vmcnt(2)
	v_mov_b32_e32 v19, v6
	v_mov_b32_e32 v6, v3
	v_mov_b32_e32 v2, v4
	v_mov_b32_e32 v3, v8
	v_mov_b32_e32 v8, v5
	s_waitcnt vmcnt(1)
	v_mov_b32_e32 v4, v10
	s_waitcnt vmcnt(0)
	v_mov_b32_e32 v5, v14
	v_mov_b32_e32 v14, v11
	v_pk_add_f32 v[6:7], v[18:19], v[6:7]
	v_mov_b32_e32 v10, v12
	v_mov_b32_e32 v11, v16
	v_pk_add_f32 v[4:5], v[4:5], v[14:15]
	v_pk_add_f32 v[2:3], v[2:3], v[6:7]
	v_mov_b32_e32 v16, v13
	v_pk_add_f32 v[4:5], v[10:11], v[4:5]
	v_pk_add_f32 v[2:3], v[8:9], v[2:3]
	v_pk_add_f32 v[4:5], v[16:17], v[4:5]
	v_add_f32_e32 v2, v2, v3
	v_add_f32_e32 v2, v2, v4
	v_add_f32_e32 v2, v2, v5
	v_fmamk_f32 v2, v2, 0x3a800000, v206
	v_mul_f32_e32 v3, 0x4b800000, v2
	v_cmp_gt_f32_e32 vcc, s58, v2
	s_nop 1
	v_cndmask_b32_e32 v2, v2, v3, vcc
	v_rsq_f32_e32 v2, v2
	s_nop 0
	v_mul_f32_e32 v3, 0x45800000, v2
	v_cndmask_b32_e32 v2, v2, v3, vcc
	v_lshl_add_u32 v3, v198, 2, v212
	ds_write_b32 v3, v2

.LBB0_1508:
	s_bfe_u32 s4, s18, 0x20003
	s_lshr_b32 s0, s18, 5
	s_lshl_b32 s0, s0, 3
	s_and_b32 s1, s18, 7
	s_add_i32 s0, s0, s1
	s_lshl_b32 s2, s0, 8
	s_ashr_i32 s3, s2, 31
	s_ashr_i32 s5, s4, 31
	s_lshl_b64 s[0:1], s[4:5], 19
	s_lshl_b64 s[6:7], s[2:3], 11
	v_readlane_b32 s8, v252, 31
	v_readlane_b32 s9, v252, 32
	s_add_u32 s8, s8, s6
	v_mov_b32_e32 v34, v174
	s_addc_u32 s9, s9, s7
	s_add_u32 s10, s14, s0
	v_lshlrev_b32_e32 v0, 4, v34
	v_ashrrev_i32_e32 v35, 3, v34
	v_and_b32_e32 v0, 0x70, v0
	s_addc_u32 s11, s15, s1
	v_lshl_or_b32 v0, v35, 11, v0
	v_lshl_add_u64 v[26:27], s[10:11], 0, v[0:1]
	v_add_co_u32_e32 v10, vcc, s52, v26
	v_lshl_add_u64 v[28:29], s[8:9], 0, v[0:1]
	s_nop 0
	v_addc_co_u32_e32 v11, vcc, 0, v27, vcc
	v_add_co_u32_e32 v14, vcc, s52, v28
	global_load_dwordx4 v[2:5], v0, s[10:11]
	global_load_dwordx4 v[6:9], v0, s[8:9]
	v_addc_co_u32_e32 v15, vcc, 0, v29, vcc
	v_add_co_u32_e32 v18, vcc, s56, v26
	global_load_dwordx4 v[10:13], v[10:11], off
	s_nop 0
	global_load_dwordx4 v[14:17], v[14:15], off
	v_addc_co_u32_e32 v19, vcc, 0, v27, vcc
	v_add_co_u32_e32 v22, vcc, s56, v28
	v_readlane_b32 s8, v250, 9
	s_nop 0
	v_addc_co_u32_e32 v23, vcc, 0, v29, vcc
	v_add_co_u32_e32 v26, vcc, s57, v26
	global_load_dwordx4 v[18:21], v[18:19], off
	s_nop 0
	global_load_dwordx4 v[22:25], v[22:23], off
	v_addc_co_u32_e32 v27, vcc, 0, v27, vcc
	v_add_co_u32_e32 v30, vcc, s57, v28
	v_lshrrev_b32_e32 v36, 1, v35
	s_nop 0
	v_addc_co_u32_e32 v31, vcc, 0, v29, vcc
	global_load_dwordx4 v[26:29], v[26:27], off
	s_nop 0
	global_load_dwordx4 v[30:33], v[30:31], off
	v_readlane_b32 s10, v250, 11
	v_xor_b32_e32 v34, v36, v34
	v_readlane_b32 s11, v250, 12
	s_add_u32 s6, s10, s6
	v_lshlrev_b32_e32 v35, 7, v35
	v_lshlrev_b32_e32 v34, 4, v34
	s_addc_u32 s7, s11, s7
	v_mov_b32_e32 v82, 0
	v_and_or_b32 v198, v34, s55, v35
	v_readlane_b32 s9, v250, 10
	s_add_u32 s8, s16, s0
	s_mov_b32 s3, 0
	v_mov_b32_e32 v83, v82
	v_mov_b32_e32 v84, v82
	v_mov_b32_e32 v85, v82
	v_mov_b32_e32 v86, v82
	v_mov_b32_e32 v87, v82
	v_mov_b32_e32 v88, v82
	v_mov_b32_e32 v89, v82
	v_mov_b32_e32 v90, v82
	v_mov_b32_e32 v91, v82
	v_mov_b32_e32 v92, v82
	v_mov_b32_e32 v93, v82
	v_mov_b32_e32 v94, v82
	v_mov_b32_e32 v95, v82
	v_mov_b32_e32 v96, v82
	v_mov_b32_e32 v97, v82
	v_mov_b32_e32 v66, v82
	v_add_u32_e32 v199, 0x10000, v198
	s_addc_u32 s9, s17, s1
	v_mov_b32_e32 v67, v82
	v_mov_b32_e32 v68, v82
	v_mov_b32_e32 v69, v82
	v_mov_b32_e32 v70, v82
	v_mov_b32_e32 v71, v82
	v_mov_b32_e32 v72, v82
	v_mov_b32_e32 v73, v82
	v_mov_b32_e32 v74, v82
	v_mov_b32_e32 v75, v82
	v_mov_b32_e32 v76, v82
	v_mov_b32_e32 v77, v82
	v_mov_b32_e32 v78, v82
	v_mov_b32_e32 v79, v82
	v_mov_b32_e32 v80, v82
	v_mov_b32_e32 v81, v82
	v_mov_b32_e32 v114, v82
	v_mov_b32_e32 v115, v82
	v_mov_b32_e32 v116, v82
	v_mov_b32_e32 v117, v82
	s_waitcnt vmcnt(7)
	ds_write_b128 v198, v[2:5]
	s_waitcnt vmcnt(6)
	ds_write_b128 v199, v[6:9]
	s_waitcnt vmcnt(5)
	ds_write_b128 v198, v[10:13] offset:8192
	s_waitcnt vmcnt(4)
	ds_write_b128 v199, v[14:17] offset:8192
	s_waitcnt vmcnt(3)
	ds_write_b128 v198, v[18:21] offset:16384
	s_waitcnt vmcnt(2)
	ds_write_b128 v199, v[22:25] offset:16384
	s_waitcnt vmcnt(1)
	ds_write_b128 v198, v[26:29] offset:24576
	s_waitcnt vmcnt(0)
	ds_write_b128 v199, v[30:33] offset:24576
	v_mov_b32_e32 v18, v82
	v_mov_b32_e32 v19, v82
	v_mov_b32_e32 v20, v82
	v_mov_b32_e32 v21, v82
	v_mov_b32_e32 v22, v82
	v_mov_b32_e32 v23, v82
	v_mov_b32_e32 v24, v82
	v_mov_b32_e32 v25, v82
	v_mov_b32_e32 v26, v82
	v_mov_b32_e32 v27, v82
	v_mov_b32_e32 v28, v82
	v_mov_b32_e32 v29, v82
	v_mov_b32_e32 v30, v82
	v_mov_b32_e32 v31, v82
	v_mov_b32_e32 v32, v82
	v_mov_b32_e32 v33, v82
	v_mov_b32_e32 v2, v82
	v_mov_b32_e32 v3, v82
	v_mov_b32_e32 v4, v82
	v_mov_b32_e32 v5, v82
	v_mov_b32_e32 v6, v82
	v_mov_b32_e32 v7, v82
	v_mov_b32_e32 v8, v82
	v_mov_b32_e32 v9, v82
	v_mov_b32_e32 v10, v82
	v_mov_b32_e32 v11, v82
	v_mov_b32_e32 v12, v82
	v_mov_b32_e32 v13, v82
	v_mov_b32_e32 v14, v82
	v_mov_b32_e32 v15, v82
	v_mov_b32_e32 v16, v82
	v_mov_b32_e32 v17, v82
	v_mov_b32_e32 v118, v82
	v_mov_b32_e32 v119, v82
	v_mov_b32_e32 v120, v82
	v_mov_b32_e32 v121, v82
	v_mov_b32_e32 v122, v82
	v_mov_b32_e32 v123, v82
	v_mov_b32_e32 v124, v82
	v_mov_b32_e32 v125, v82
	v_mov_b32_e32 v126, v82
	v_mov_b32_e32 v127, v82
	v_mov_b32_e32 v128, v82
	v_mov_b32_e32 v129, v82
	v_mov_b32_e32 v98, v82
	v_mov_b32_e32 v99, v82
	v_mov_b32_e32 v100, v82
	v_mov_b32_e32 v101, v82
	v_mov_b32_e32 v102, v82
	v_mov_b32_e32 v103, v82
	v_mov_b32_e32 v104, v82
	v_mov_b32_e32 v105, v82
	v_mov_b32_e32 v106, v82
	v_mov_b32_e32 v107, v82
	v_mov_b32_e32 v108, v82
	v_mov_b32_e32 v109, v82
	v_mov_b32_e32 v110, v82
	v_mov_b32_e32 v111, v82
	v_mov_b32_e32 v112, v82
	v_mov_b32_e32 v113, v82
	v_mov_b32_e32 v50, v82
	v_mov_b32_e32 v51, v82
	v_mov_b32_e32 v52, v82
	v_mov_b32_e32 v53, v82
	v_mov_b32_e32 v54, v82
	v_mov_b32_e32 v55, v82
	v_mov_b32_e32 v56, v82
	v_mov_b32_e32 v57, v82
	v_mov_b32_e32 v58, v82
	v_mov_b32_e32 v59, v82
	v_mov_b32_e32 v60, v82
	v_mov_b32_e32 v61, v82
	v_mov_b32_e32 v62, v82
	v_mov_b32_e32 v63, v82
	v_mov_b32_e32 v64, v82
	v_mov_b32_e32 v65, v82
	v_mov_b32_e32 v34, v82
	v_mov_b32_e32 v35, v82
	v_mov_b32_e32 v36, v82
	v_mov_b32_e32 v37, v82
	v_mov_b32_e32 v38, v82
	v_mov_b32_e32 v39, v82
	v_mov_b32_e32 v40, v82
	v_mov_b32_e32 v41, v82
	v_mov_b32_e32 v42, v82
	v_mov_b32_e32 v43, v82
	v_mov_b32_e32 v44, v82
	v_mov_b32_e32 v45, v82
	v_mov_b32_e32 v46, v82
	v_mov_b32_e32 v47, v82
	v_mov_b32_e32 v48, v82
	v_mov_b32_e32 v49, v82
	s_waitcnt lgkmcnt(0)
	s_barrier
	s_branch .LBB0_1510

.LBB0_1602:
	s_bfe_u32 s6, s35, 0x30003
	s_and_b32 s0, s35, 1
	s_lshl_b32 s0, s0, 3
	s_or_b32 s6, s6, s0
	s_bfe_u32 s0, s35, 0x20006
	s_bfe_u32 s1, s35, 0x20001
	s_lshl_b32 s1, s1, 2
	s_or_b32 s0, s0, s1
	s_lshr_b32 s1, s35, 8
	s_lshl_b32 s1, s1, 4
	s_or_b32 s0, s0, s1
	s_lshl_b32 s4, s0, 8
	s_ashr_i32 s5, s4, 31
	s_ashr_i32 s7, s6, 31
	s_lshl_b64 s[0:1], s[6:7], 19
	s_lshl_b64 s[8:9], s[4:5], 11
	v_readlane_b32 s10, v250, 44
	v_readlane_b32 s11, v250, 45
	s_add_u32 s10, s10, s8
	v_mov_b32_e32 v34, v172
	s_addc_u32 s11, s11, s9
	s_add_u32 s12, s31, s0
	v_lshlrev_b32_e32 v0, 4, v34
	v_ashrrev_i32_e32 v35, 3, v34
	v_and_b32_e32 v0, 0x70, v0
	s_addc_u32 s13, s34, s1
	v_lshl_or_b32 v0, v35, 11, v0
	v_lshl_add_u64 v[26:27], s[12:13], 0, v[0:1]
	v_add_co_u32_e32 v10, vcc, s52, v26
	v_lshl_add_u64 v[28:29], s[10:11], 0, v[0:1]
	s_nop 0
	v_addc_co_u32_e32 v11, vcc, 0, v27, vcc
	v_add_co_u32_e32 v14, vcc, s52, v28
	global_load_dwordx4 v[2:5], v0, s[12:13]
	global_load_dwordx4 v[6:9], v0, s[10:11]
	v_addc_co_u32_e32 v15, vcc, 0, v29, vcc
	v_add_co_u32_e32 v18, vcc, s56, v26
	global_load_dwordx4 v[10:13], v[10:11], off
	s_nop 0
	global_load_dwordx4 v[14:17], v[14:15], off
	v_addc_co_u32_e32 v19, vcc, 0, v27, vcc
	v_add_co_u32_e32 v22, vcc, s56, v28
	v_lshrrev_b32_e32 v36, 1, v35
	s_nop 0
	v_addc_co_u32_e32 v23, vcc, 0, v29, vcc
	v_add_co_u32_e32 v26, vcc, s57, v26
	global_load_dwordx4 v[18:21], v[18:19], off
	s_nop 0
	global_load_dwordx4 v[22:25], v[22:23], off
	v_addc_co_u32_e32 v27, vcc, 0, v27, vcc
	v_add_co_u32_e32 v30, vcc, s57, v28
	v_xor_b32_e32 v34, v36, v34
	s_nop 0
	v_addc_co_u32_e32 v31, vcc, 0, v29, vcc
	global_load_dwordx4 v[26:29], v[26:27], off
	s_nop 0
	global_load_dwordx4 v[30:33], v[30:31], off
	v_lshlrev_b32_e32 v35, 7, v35
	v_lshlrev_b32_e32 v34, 4, v34
	v_and_or_b32 v194, v34, s55, v35
	v_add_u32_e32 v195, 0x10000, v194
	s_waitcnt vmcnt(7)
	ds_write_b128 v194, v[2:5]
	s_waitcnt vmcnt(6)
	ds_write_b128 v195, v[6:9]
	s_waitcnt vmcnt(5)
	ds_write_b128 v194, v[10:13] offset:8192
	s_waitcnt vmcnt(4)
	ds_write_b128 v195, v[14:17] offset:8192
	s_waitcnt vmcnt(3)
	ds_write_b128 v194, v[18:21] offset:16384
	s_waitcnt vmcnt(2)
	ds_write_b128 v195, v[22:25] offset:16384
	s_waitcnt vmcnt(1)
	ds_write_b128 v194, v[26:29] offset:24576
	s_waitcnt vmcnt(0)
	ds_write_b128 v195, v[30:33] offset:24576
	s_waitcnt lgkmcnt(0)
	s_barrier
	s_and_saveexec_b64 s[10:11], s[2:3]
	s_cbranch_execz .LBB0_1604
	v_add_u32_e32 v2, s4, v172
	v_ashrrev_i32_e32 v3, 31, v2
	v_readlane_b32 s12, v250, 46
	v_lshlrev_b64 v[2:3], 6, v[2:3]
	v_readlane_b32 s13, v250, 47
	s_nop 1
	v_lshl_add_u64 v[14:15], s[12:13], 0, v[2:3]
	global_load_dwordx4 v[2:5], v[14:15], off
	global_load_dwordx4 v[6:9], v[14:15], off offset:16
	global_load_dwordx4 v[10:13], v[14:15], off offset:32
	s_nop 0
	global_load_dwordx4 v[14:17], v[14:15], off offset:48
	s_waitcnt vmcnt(3)
	v_mov_b32_e32 v18, v2
	s_waitcnt vmcnt(2)
	v_mov_b32_e32 v19, v6
	v_mov_b32_e32 v6, v3
	v_mov_b32_e32 v2, v4
	v_mov_b32_e32 v3, v8
	v_mov_b32_e32 v8, v5
	s_waitcnt vmcnt(1)
	v_mov_b32_e32 v4, v10
	s_waitcnt vmcnt(0)
	v_mov_b32_e32 v5, v14
	v_mov_b32_e32 v14, v11
	v_pk_add_f32 v[6:7], v[18:19], v[6:7]
	v_mov_b32_e32 v10, v12
	v_mov_b32_e32 v11, v16
	v_pk_add_f32 v[4:5], v[4:5], v[14:15]
	v_pk_add_f32 v[2:3], v[2:3], v[6:7]
	v_mov_b32_e32 v16, v13
	v_pk_add_f32 v[4:5], v[10:11], v[4:5]
	v_pk_add_f32 v[2:3], v[8:9], v[2:3]
	v_pk_add_f32 v[4:5], v[16:17], v[4:5]
	v_add_f32_e32 v2, v2, v3
	v_add_f32_e32 v2, v2, v4
	v_add_f32_e32 v2, v2, v5
	v_fmamk_f32 v2, v2, 0x3a800000, v206
	v_mul_f32_e32 v3, 0x4b800000, v2
	v_cmp_gt_f32_e32 vcc, s58, v2
	s_nop 1
	v_cndmask_b32_e32 v2, v2, v3, vcc
	v_rsq_f32_e32 v2, v2
	s_nop 0
	v_mul_f32_e32 v3, 0x45800000, v2
	v_cndmask_b32_e32 v2, v2, v3, vcc
	ds_write_b32 v178, v2

.LBB0_1678:
	s_bfe_u32 s4, s30, 0x20003
	s_lshr_b32 s0, s30, 5
	s_lshl_b32 s0, s0, 3
	s_and_b32 s1, s30, 7
	s_add_i32 s0, s0, s1
	s_lshl_b32 s2, s0, 8
	s_ashr_i32 s3, s2, 31
	s_ashr_i32 s5, s4, 31
	s_lshl_b64 s[0:1], s[4:5], 21
	s_lshl_b64 s[6:7], s[2:3], 13
	v_readlane_b32 s8, v250, 48
	v_readlane_b32 s9, v250, 49
	s_add_u32 s8, s8, s6
	v_mov_b32_e32 v34, v172
	s_addc_u32 s9, s9, s7
	s_add_u32 s10, s28, s0
	v_lshlrev_b32_e32 v0, 4, v34
	v_ashrrev_i32_e32 v35, 3, v34
	v_and_b32_e32 v0, 0x70, v0
	s_addc_u32 s11, s29, s1
	v_lshl_or_b32 v0, v35, 13, v0
	v_lshl_add_u64 v[26:27], s[10:11], 0, v[0:1]
	s_mov_b32 s3, 0x80000
	v_add_co_u32_e32 v10, vcc, s3, v26
	v_lshl_add_u64 v[28:29], s[8:9], 0, v[0:1]
	s_nop 0
	v_addc_co_u32_e32 v11, vcc, 0, v27, vcc
	v_add_co_u32_e32 v14, vcc, s3, v28
	s_mov_b32 s3, 0x100000
	s_nop 0
	v_addc_co_u32_e32 v15, vcc, 0, v29, vcc
	v_add_co_u32_e32 v18, vcc, s3, v26
	global_load_dwordx4 v[2:5], v0, s[10:11]
	global_load_dwordx4 v[6:9], v0, s[8:9]
	v_addc_co_u32_e32 v19, vcc, 0, v27, vcc
	v_add_co_u32_e32 v22, vcc, s3, v28
	s_mov_b32 s3, 0x180000
	s_nop 0
	v_addc_co_u32_e32 v23, vcc, 0, v29, vcc
	v_add_co_u32_e32 v26, vcc, s3, v26
	global_load_dwordx4 v[10:13], v[10:11], off
	s_nop 0
	global_load_dwordx4 v[14:17], v[14:15], off
	v_addc_co_u32_e32 v27, vcc, 0, v27, vcc
	v_add_co_u32_e32 v30, vcc, s3, v28
	global_load_dwordx4 v[18:21], v[18:19], off
	s_nop 0
	global_load_dwordx4 v[22:25], v[22:23], off
	v_addc_co_u32_e32 v31, vcc, 0, v29, vcc
	global_load_dwordx4 v[26:29], v[26:27], off
	s_nop 0
	global_load_dwordx4 v[30:33], v[30:31], off
	v_readlane_b32 s8, v250, 9
	v_readlane_b32 s10, v250, 11
	v_readlane_b32 s11, v250, 12
	s_add_u32 s6, s10, s6
	s_addc_u32 s7, s11, s7
	v_readlane_b32 s5, v251, 9
	v_readlane_b32 s9, v250, 10
	s_add_u32 s8, s5, s0
	v_readlane_b32 s5, v251, 10
	s_addc_u32 s9, s5, s1
	v_readlane_b32 s5, v251, 11
	s_add_u32 s10, s5, s0
	v_readlane_b32 s5, v251, 12
	s_addc_u32 s11, s5, s1
	v_readlane_b32 s5, v251, 13
	s_add_u32 s12, s5, s0
	v_readlane_b32 s5, v251, 14
	s_addc_u32 s13, s5, s1
	v_readlane_b32 s5, v251, 15
	s_add_u32 s14, s5, s0
	v_readlane_b32 s5, v251, 16
	s_addc_u32 s15, s5, s1
	v_readlane_b32 s5, v251, 17
	s_add_u32 s16, s5, s0
	v_readlane_b32 s5, v251, 18
	s_addc_u32 s17, s5, s1
	v_readlane_b32 s5, v251, 19
	s_add_u32 s18, s5, s0
	v_readlane_b32 s5, v251, 20
	v_lshrrev_b32_e32 v36, 1, v35
	s_addc_u32 s19, s5, s1
	v_readlane_b32 s5, v251, 21
	v_xor_b32_e32 v34, v36, v34
	s_add_u32 s20, s5, s0
	v_readlane_b32 s5, v251, 22
	v_lshlrev_b32_e32 v35, 7, v35
	v_lshlrev_b32_e32 v34, 4, v34
	s_addc_u32 s21, s5, s1
	v_readlane_b32 s5, v251, 23
	v_mov_b32_e32 v66, 0
	v_and_or_b32 v192, v34, s55, v35
	s_add_u32 s22, s5, s0
	v_readlane_b32 s0, v251, 24
	s_mov_b32 s3, 0
	v_mov_b32_e32 v67, v66
	v_mov_b32_e32 v68, v66
	v_add_u32_e32 v193, 0x10000, v192
	s_addc_u32 s23, s0, s1
	s_waitcnt vmcnt(7)
	ds_write_b128 v192, v[2:5]
	s_waitcnt vmcnt(6)
	ds_write_b128 v193, v[6:9]
	s_waitcnt vmcnt(5)
	ds_write_b128 v192, v[10:13] offset:8192
	s_waitcnt vmcnt(4)
	ds_write_b128 v193, v[14:17] offset:8192
	s_waitcnt vmcnt(3)
	ds_write_b128 v192, v[18:21] offset:16384
	s_waitcnt vmcnt(2)
	ds_write_b128 v193, v[22:25] offset:16384
	s_waitcnt vmcnt(1)
	ds_write_b128 v192, v[26:29] offset:24576
	s_waitcnt vmcnt(0)
	ds_write_b128 v193, v[30:33] offset:24576
	v_mov_b32_e32 v69, v66
	v_mov_b32_e32 v70, v66
	v_mov_b32_e32 v71, v66
	v_mov_b32_e32 v72, v66
	v_mov_b32_e32 v73, v66
	v_mov_b32_e32 v74, v66
	v_mov_b32_e32 v75, v66
	v_mov_b32_e32 v76, v66
	v_mov_b32_e32 v77, v66
	v_mov_b32_e32 v78, v66
	v_mov_b32_e32 v79, v66
	v_mov_b32_e32 v80, v66
	v_mov_b32_e32 v81, v66
	v_mov_b32_e32 v82, v66
	v_mov_b32_e32 v83, v66
	v_mov_b32_e32 v84, v66
	v_mov_b32_e32 v85, v66
	v_mov_b32_e32 v86, v66
	v_mov_b32_e32 v87, v66
	v_mov_b32_e32 v88, v66
	v_mov_b32_e32 v89, v66
	v_mov_b32_e32 v90, v66
	v_mov_b32_e32 v91, v66
	v_mov_b32_e32 v92, v66
	v_mov_b32_e32 v93, v66
	v_mov_b32_e32 v94, v66
	v_mov_b32_e32 v95, v66
	v_mov_b32_e32 v96, v66
	v_mov_b32_e32 v97, v66
	v_mov_b32_e32 v18, v66
	v_mov_b32_e32 v19, v66
	v_mov_b32_e32 v20, v66
	v_mov_b32_e32 v21, v66
	v_mov_b32_e32 v22, v66
	v_mov_b32_e32 v23, v66
	v_mov_b32_e32 v24, v66
	v_mov_b32_e32 v25, v66
	v_mov_b32_e32 v26, v66
	v_mov_b32_e32 v27, v66
	v_mov_b32_e32 v28, v66
	v_mov_b32_e32 v29, v66
	v_mov_b32_e32 v30, v66
	v_mov_b32_e32 v31, v66
	v_mov_b32_e32 v32, v66
	v_mov_b32_e32 v33, v66
	v_mov_b32_e32 v2, v66
	v_mov_b32_e32 v3, v66
	v_mov_b32_e32 v4, v66
	v_mov_b32_e32 v5, v66
	v_mov_b32_e32 v6, v66
	v_mov_b32_e32 v7, v66
	v_mov_b32_e32 v8, v66
	v_mov_b32_e32 v9, v66
	v_mov_b32_e32 v10, v66
	v_mov_b32_e32 v11, v66
	v_mov_b32_e32 v12, v66
	v_mov_b32_e32 v13, v66
	v_mov_b32_e32 v14, v66
	v_mov_b32_e32 v15, v66
	v_mov_b32_e32 v16, v66
	v_mov_b32_e32 v17, v66
	v_mov_b32_e32 v114, v66
	v_mov_b32_e32 v115, v66
	v_mov_b32_e32 v116, v66
	v_mov_b32_e32 v117, v66
	v_mov_b32_e32 v118, v66
	v_mov_b32_e32 v119, v66
	v_mov_b32_e32 v120, v66
	v_mov_b32_e32 v121, v66
	v_mov_b32_e32 v122, v66
	v_mov_b32_e32 v123, v66
	v_mov_b32_e32 v124, v66
	v_mov_b32_e32 v125, v66
	v_mov_b32_e32 v126, v66
	v_mov_b32_e32 v127, v66
	v_mov_b32_e32 v128, v66
	v_mov_b32_e32 v129, v66
	v_mov_b32_e32 v98, v66
	v_mov_b32_e32 v99, v66
	v_mov_b32_e32 v100, v66
	v_mov_b32_e32 v101, v66
	v_mov_b32_e32 v102, v66
	v_mov_b32_e32 v103, v66
	v_mov_b32_e32 v104, v66
	v_mov_b32_e32 v105, v66
	v_mov_b32_e32 v106, v66
	v_mov_b32_e32 v107, v66
	v_mov_b32_e32 v108, v66
	v_mov_b32_e32 v109, v66
	v_mov_b32_e32 v110, v66
	v_mov_b32_e32 v111, v66
	v_mov_b32_e32 v112, v66
	v_mov_b32_e32 v113, v66
	v_mov_b32_e32 v50, v66
	v_mov_b32_e32 v51, v66
	v_mov_b32_e32 v52, v66
	v_mov_b32_e32 v53, v66
	v_mov_b32_e32 v54, v66
	v_mov_b32_e32 v55, v66
	v_mov_b32_e32 v56, v66
	v_mov_b32_e32 v57, v66
	v_mov_b32_e32 v58, v66
	v_mov_b32_e32 v59, v66
	v_mov_b32_e32 v60, v66
	v_mov_b32_e32 v61, v66
	v_mov_b32_e32 v62, v66
	v_mov_b32_e32 v63, v66
	v_mov_b32_e32 v64, v66
	v_mov_b32_e32 v65, v66
	v_mov_b32_e32 v34, v66
	v_mov_b32_e32 v35, v66
	v_mov_b32_e32 v36, v66
	v_mov_b32_e32 v37, v66
	v_mov_b32_e32 v38, v66
	v_mov_b32_e32 v39, v66
	v_mov_b32_e32 v40, v66
	v_mov_b32_e32 v41, v66
	v_mov_b32_e32 v42, v66
	v_mov_b32_e32 v43, v66
	v_mov_b32_e32 v44, v66
	v_mov_b32_e32 v45, v66
	v_mov_b32_e32 v46, v66
	v_mov_b32_e32 v47, v66
	v_mov_b32_e32 v48, v66
	v_mov_b32_e32 v49, v66
	s_waitcnt lgkmcnt(0)
	s_barrier
	s_branch .LBB0_1680
